# indexer first-digit histogram: branch-free path for tiles fully below the diagonal
# speedup vs baseline: 1.0267x; 1.0020x over previous
; #define LAS __attribute__((address_space(3)))
; __device__ __forceinline__ void phaseB(const Params& p, LAS unsigned char* lds, int wv) {
;     ...
;             const int qg = wid & 1, ks = wid >> 1;
;             const LAS float* wp = (const LAS float*)(lds + B_TOFF) + (32 * qg + r32) * 8;
;             const LAS unsigned char* qp = lds + (32 * qg + r32) * B_QROW + hi * 16;
;             LAS unsigned* hrow = hist + (32 * qg + r32) * B_HROW;
;             const int tq = q0 + 32 * qg + r32;
; #pragma unroll 1
;             for (int rep1 = 0; rep1 < REPK; ++rep1)
; #pragma unroll 1
;             for (int kt = ks; kt < NT; kt += 4) {
.LBB0_404:
	s_or_b64 exec, exec, s[0:1]
	s_ashr_i32 s4, s5, 7
	s_cmp_gt_i32 s4, s33
	s_waitcnt lgkmcnt(0)
	s_barrier
	s_cbranch_scc1 .LBB0_475
	s_lshr_b32 s0, s5, 1
	v_and_b32_e32 v4, 31, v0
	s_and_b32 s0, s0, 32
	v_bfe_u32 v5, v0, 5, 1
	v_or_b32_e32 v1, s0, v4
	v_mul_u32_u24_e32 v3, 0x410, v1
	v_lshlrev_b32_e32 v2, 4, v5
	s_add_i32 s1, 0, 0x10400
	v_add3_u32 v132, 0, v3, v2
	v_mov_b32_e32 v3, s1
	s_movk_i32 s1, 0x404
	v_mad_u32_u24 v133, v1, s1, v3
	v_readlane_b32 s1, v247, 42
	v_lshrrev_b32_e32 v6, 1, v0
	v_and_b32_e32 v6, 4, v6
	v_or_b32_e32 v3, s1, v4
	v_or_b32_e32 v134, s0, v3
	v_lshlrev_b32_e32 v3, 1, v0
	v_and_b32_e32 v3, 8, v3
	v_and_or_b32 v0, v0, 19, v6
	v_readlane_b32 s0, v247, 14
	v_or3_b32 v208, v0, v3, s30
	v_mov_b32_e32 v3, v209
	v_readlane_b32 s1, v247, 15
	v_lshlrev_b32_e32 v0, 14, v1
	v_mov_b32_e32 v1, v209
	v_lshl_add_u64 v[128:129], s[0:1], 0, v[2:3]
	v_readlane_b32 s0, v247, 26
	v_readlane_b32 s1, v247, 27
	s_cmp_gt_u32 s33, 3
	v_lshlrev_b32_e32 v2, 5, v5
	v_lshl_add_u64 v[0:1], s[0:1], 0, v[0:1]
	s_cselect_b64 s[0:1], -1, 0
	s_lshl_b32 s2, s5, 4
	s_and_b32 s2, s2, 0x400
	s_add_i32 s2, s2, 0
	s_add_i32 s2, s2, 0x20504
	v_lshlrev_b32_e32 v135, 3, v5
	v_lshl_add_u64 v[130:131], v[0:1], 0, v[2:3]
	v_subrev_u32_e32 v136, 32, v134
	v_lshl_add_u32 v137, v4, 5, s2
	v_readfirstlane_b32 s99, v134
	s_branch .LBB0_408

; #define LAS __attribute__((address_space(3)))
; __device__ __forceinline__ unsigned ord_key(float f) { const unsigned u = __float_as_uint(f); return u ^ ((u >> 31) ? 0xffffffffu : 0x80000000u); }
; __device__ __forceinline__ void phaseB(const Params& p, LAS unsigned char* lds, int wv) {
;     ...
;                 for (int hh = 0; hh < 8; ++hh) {
;                     const float wh = wp[hh];
;                     f32x16 s0, s1;
; #pragma unroll
;                     for (int r = 0; r < 16; ++r) { s0[r] = 0.f; s1[r] = 0.f; }
; #pragma unroll
;                     for (int ds = 0; ds < 4; ++ds) { const f16x8 qfr = *(const LAS f16x8*)(qp + hh * 128 + ds * 32);
;                         s0 = __builtin_amdgcn_mfma_f32_32x32x16_f16(kf[0][ds], qfr, s0, 0, 0, 0); s1 = __builtin_amdgcn_mfma_f32_32x32x16_f16(kf[1][ds], qfr, s1, 0, 0, 0); }
; #pragma unroll
;                     for (int r = 0; r < 16; ++r) { acc0[r] += wh * fmaxf(s0[r], 0.f); acc1[r] += wh * fmaxf(s1[r], 0.f); }
;                 }
;                 float* sp = SC + (size_t)(32 * qg + r32) * SEQ + k0 + 8 * hi;
;                 *(f32x4*)(sp) = (f32x4){acc0[0], acc0[1], acc0[2], acc0[3]}; *(f32x4*)(sp + 4) = (f32x4){acc0[4], acc0[5], acc0[6], acc0[7]};
;                 *(f32x4*)(sp + 16) = (f32x4){acc0[8], acc0[9], acc0[10], acc0[11]}; *(f32x4*)(sp + 20) = (f32x4){acc0[12], acc0[13], acc0[14], acc0[15]};
;                 *(f32x4*)(sp + 32) = (f32x4){acc1[0], acc1[1], acc1[2], acc1[3]}; *(f32x4*)(sp + 36) = (f32x4){acc1[4], acc1[5], acc1[6], acc1[7]};
;                 *(f32x4*)(sp + 48) = (f32x4){acc1[8], acc1[9], acc1[10], acc1[11]}; *(f32x4*)(sp + 52) = (f32x4){acc1[12], acc1[13], acc1[14], acc1[15]};
;                 if (q0 + 63 > 255 && rep1 == 0) {
;                     int e0 = k0 + 8 * hi; asm volatile("" : "+v"(e0));
; #pragma unroll
;                     for (int r = 0; r < 16; ++r) { const int kp0 = e0 + 16 * (r >> 3) + (r & 7);
;                         if (kp0 <= tq) atomicAdd((unsigned*)&hrow[ord_key(acc0[r]) >> 24], 1u);
;                         if (kp0 + 32 <= tq) atomicAdd((unsigned*)&hrow[ord_key(acc1[r]) >> 24], 1u); }
.LBB0_409:
	v_add_u32_e32 v139, s5, v132
	ds_read_b128 v[0:3], v139
	ds_read_b128 v[140:143], v139 offset:32
	ds_read_b128 v[48:51], v139 offset:128
	ds_read_b128 v[144:147], v139 offset:160
	s_addk_i32 s5, 0x100
	s_cmpk_eq_i32 s5, 0x400
	s_waitcnt vmcnt(7) lgkmcnt(3)
	v_mfma_f32_32x32x16_f16 v[16:31], v[96:99], v[0:3], 0
	s_waitcnt vmcnt(3)
	v_mfma_f32_32x32x16_f16 v[0:15], v[112:115], v[0:3], 0
	s_waitcnt lgkmcnt(1)
	v_mfma_f32_32x32x16_f16 v[32:47], v[96:99], v[48:51], 0
	v_mfma_f32_32x32x16_f16 v[48:63], v[112:115], v[48:51], 0
	v_mfma_f32_32x32x16_f16 v[16:31], v[100:103], v[140:143], v[16:31]
	s_waitcnt vmcnt(2)
	v_mfma_f32_32x32x16_f16 v[0:15], v[116:119], v[140:143], v[0:15]
	s_waitcnt lgkmcnt(0)
	v_mfma_f32_32x32x16_f16 v[32:47], v[100:103], v[144:147], v[32:47]
	v_mfma_f32_32x32x16_f16 v[48:63], v[116:119], v[144:147], v[48:63]
	ds_read_b128 v[140:143], v139 offset:64
	ds_read_b128 v[144:147], v139 offset:96
	s_waitcnt lgkmcnt(1)
	v_mfma_f32_32x32x16_f16 v[16:31], v[104:107], v[140:143], v[16:31]
	s_waitcnt vmcnt(1)
	v_mfma_f32_32x32x16_f16 v[0:15], v[120:123], v[140:143], v[0:15]
	ds_read_b128 v[140:143], v139 offset:192
	ds_read_b128 v[148:151], v139 offset:224
	v_add_u32_e32 v139, -4, v138
	v_add_u32_e32 v138, 8, v138
	s_waitcnt lgkmcnt(1)
	v_mfma_f32_32x32x16_f16 v[32:47], v[104:107], v[140:143], v[32:47]
	v_mfma_f32_32x32x16_f16 v[48:63], v[120:123], v[140:143], v[48:63]
	ds_read_b64 v[140:141], v139
	v_mfma_f32_32x32x16_f16 v[16:31], v[108:111], v[144:147], v[16:31]
	s_waitcnt vmcnt(0)
	v_mfma_f32_32x32x16_f16 v[0:15], v[124:127], v[144:147], v[0:15]
	s_nop 9
	v_max_f32_e32 v16, 0, v16
	v_max_f32_e32 v17, 0, v17
	v_max_f32_e32 v18, 0, v18
	v_max_f32_e32 v19, 0, v19
	v_max_f32_e32 v20, 0, v20
	v_max_f32_e32 v21, 0, v21
	v_max_f32_e32 v22, 0, v22
	s_waitcnt lgkmcnt(1)
	v_mfma_f32_32x32x16_f16 v[32:47], v[108:111], v[148:151], v[32:47]
	v_max_f32_e32 v23, 0, v23
	v_max_f32_e32 v24, 0, v24
	v_max_f32_e32 v25, 0, v25
	v_max_f32_e32 v26, 0, v26
	v_max_f32_e32 v27, 0, v27
	v_max_f32_e32 v28, 0, v28
	v_max_f32_e32 v29, 0, v29
	v_mfma_f32_32x32x16_f16 v[48:63], v[124:127], v[148:151], v[48:63]
	v_max_f32_e32 v30, 0, v30
	v_max_f32_e32 v31, 0, v31
	v_max_f32_e32 v0, 0, v0
	v_max_f32_e32 v1, 0, v1
	v_max_f32_e32 v2, 0, v2
	v_max_f32_e32 v3, 0, v3
	v_max_f32_e32 v4, 0, v4
	v_max_f32_e32 v5, 0, v5
	v_max_f32_e32 v6, 0, v6
	v_max_f32_e32 v7, 0, v7
	v_max_f32_e32 v8, 0, v8
	v_max_f32_e32 v9, 0, v9
	v_max_f32_e32 v10, 0, v10
	v_max_f32_e32 v11, 0, v11
	v_max_f32_e32 v12, 0, v12
	v_max_f32_e32 v13, 0, v13
	v_max_f32_e32 v14, 0, v14
	v_max_f32_e32 v15, 0, v15
	v_max_f32_e32 v32, 0, v32
	v_max_f32_e32 v33, 0, v33
	v_max_f32_e32 v34, 0, v34
	v_max_f32_e32 v35, 0, v35
	v_max_f32_e32 v36, 0, v36
	v_max_f32_e32 v37, 0, v37
	v_max_f32_e32 v38, 0, v38
	v_max_f32_e32 v39, 0, v39
	v_max_f32_e32 v40, 0, v40
	v_max_f32_e32 v41, 0, v41
	v_max_f32_e32 v42, 0, v42
	v_max_f32_e32 v43, 0, v43
	v_max_f32_e32 v44, 0, v44
	v_max_f32_e32 v45, 0, v45
	v_max_f32_e32 v46, 0, v46
	v_max_f32_e32 v47, 0, v47
	v_max_f32_e32 v48, 0, v48
	v_max_f32_e32 v49, 0, v49
	v_max_f32_e32 v50, 0, v50
	v_max_f32_e32 v51, 0, v51
	v_max_f32_e32 v52, 0, v52
	v_max_f32_e32 v53, 0, v53
	v_max_f32_e32 v54, 0, v54
	v_max_f32_e32 v55, 0, v55
	v_max_f32_e32 v56, 0, v56
	v_max_f32_e32 v57, 0, v57
	v_max_f32_e32 v58, 0, v58
	v_max_f32_e32 v59, 0, v59
	v_max_f32_e32 v60, 0, v60
	v_max_f32_e32 v61, 0, v61
	v_max_f32_e32 v62, 0, v62
	v_max_f32_e32 v63, 0, v63
	s_waitcnt lgkmcnt(0)
	v_pk_fma_f32 v[88:89], v[140:141], v[16:17], v[88:89] op_sel_hi:[0,1,1]
	v_pk_fma_f32 v[92:93], v[140:141], v[0:1], v[92:93] op_sel_hi:[0,1,1]
	v_pk_fma_f32 v[90:91], v[140:141], v[18:19], v[90:91] op_sel_hi:[0,1,1]
	v_pk_fma_f32 v[94:95], v[140:141], v[2:3], v[94:95] op_sel_hi:[0,1,1]
	v_pk_fma_f32 v[80:81], v[140:141], v[20:21], v[80:81] op_sel_hi:[0,1,1]
	v_pk_fma_f32 v[84:85], v[140:141], v[4:5], v[84:85] op_sel_hi:[0,1,1]
	v_pk_fma_f32 v[82:83], v[140:141], v[22:23], v[82:83] op_sel_hi:[0,1,1]
	v_pk_fma_f32 v[86:87], v[140:141], v[6:7], v[86:87] op_sel_hi:[0,1,1]
	v_pk_fma_f32 v[72:73], v[140:141], v[24:25], v[72:73] op_sel_hi:[0,1,1]
	v_pk_fma_f32 v[76:77], v[140:141], v[8:9], v[76:77] op_sel_hi:[0,1,1]
	v_pk_fma_f32 v[74:75], v[140:141], v[26:27], v[74:75] op_sel_hi:[0,1,1]
	v_pk_fma_f32 v[78:79], v[140:141], v[10:11], v[78:79] op_sel_hi:[0,1,1]
	v_pk_fma_f32 v[64:65], v[140:141], v[28:29], v[64:65] op_sel_hi:[0,1,1]
	v_pk_fma_f32 v[68:69], v[140:141], v[12:13], v[68:69] op_sel_hi:[0,1,1]
	v_pk_fma_f32 v[66:67], v[140:141], v[30:31], v[66:67] op_sel_hi:[0,1,1]
	v_pk_fma_f32 v[70:71], v[140:141], v[14:15], v[70:71] op_sel_hi:[0,1,1]
	v_pk_fma_f32 v[88:89], v[140:141], v[32:33], v[88:89] op_sel:[1,0,0]
	v_pk_fma_f32 v[92:93], v[140:141], v[48:49], v[92:93] op_sel:[1,0,0]
	v_pk_fma_f32 v[90:91], v[140:141], v[34:35], v[90:91] op_sel:[1,0,0]
	v_pk_fma_f32 v[94:95], v[140:141], v[50:51], v[94:95] op_sel:[1,0,0]
	v_pk_fma_f32 v[80:81], v[140:141], v[36:37], v[80:81] op_sel:[1,0,0]
	v_pk_fma_f32 v[84:85], v[140:141], v[52:53], v[84:85] op_sel:[1,0,0]
	v_pk_fma_f32 v[82:83], v[140:141], v[38:39], v[82:83] op_sel:[1,0,0]
	v_pk_fma_f32 v[86:87], v[140:141], v[54:55], v[86:87] op_sel:[1,0,0]
	v_pk_fma_f32 v[72:73], v[140:141], v[40:41], v[72:73] op_sel:[1,0,0]
	v_pk_fma_f32 v[76:77], v[140:141], v[56:57], v[76:77] op_sel:[1,0,0]
	v_pk_fma_f32 v[74:75], v[140:141], v[42:43], v[74:75] op_sel:[1,0,0]
	v_pk_fma_f32 v[78:79], v[140:141], v[58:59], v[78:79] op_sel:[1,0,0]
	v_pk_fma_f32 v[64:65], v[140:141], v[44:45], v[64:65] op_sel:[1,0,0]
	v_pk_fma_f32 v[68:69], v[140:141], v[60:61], v[68:69] op_sel:[1,0,0]
	v_pk_fma_f32 v[66:67], v[140:141], v[46:47], v[66:67] op_sel:[1,0,0]
	v_pk_fma_f32 v[70:71], v[140:141], v[62:63], v[70:71] op_sel:[1,0,0]
	s_cbranch_scc0 .LBB0_409
	v_lshl_add_u64 v[0:1], s[2:3], 2, v[130:131]
	s_and_b64 vcc, exec, s[0:1]
	global_store_dwordx4 v[0:1], v[88:91], off
	global_store_dwordx4 v[0:1], v[80:83], off offset:16
	global_store_dwordx4 v[0:1], v[72:75], off offset:64
	global_store_dwordx4 v[0:1], v[64:67], off offset:80
	global_store_dwordx4 v[0:1], v[92:95], off offset:128
	global_store_dwordx4 v[0:1], v[84:87], off offset:144
	global_store_dwordx4 v[0:1], v[76:79], off offset:192
	global_store_dwordx4 v[0:1], v[68:71], off offset:208
	s_cbranch_vccz .LBB0_407
	s_add_i32 s100, s2, 63
	s_cmp_le_i32 s100, s99
	s_cbranch_scc1 .Lb1_fast_hist
	v_or_b32_e32 v0, s2, v135
	s_nop 0
	v_cmp_le_i32_e32 vcc, v0, v134
	s_and_saveexec_b64 s[2:3], vcc
	s_cbranch_execz .LBB0_413
	v_cmp_lt_i32_e32 vcc, -1, v88
	s_nop 1
	v_cndmask_b32_e32 v1, -1, v230, vcc
	v_xor_b32_e32 v1, v1, v88
	v_lshrrev_b32_e32 v1, 24, v1
	v_lshl_add_u32 v1, v1, 2, v133
	ds_add_u32 v1, v228

; __device__ __forceinline__ unsigned ord_key(float f) { const unsigned u = __float_as_uint(f); return u ^ ((u >> 31) ? 0xffffffffu : 0x80000000u); }
; __device__ __forceinline__ void phaseB(const Params& p, LAS unsigned char* lds, int wv) {
;     ...
;                 if (q0 + 63 > 255 && rep1 == 0) {
;                     int e0 = k0 + 8 * hi; asm volatile("" : "+v"(e0));
; #pragma unroll
;                     for (int r = 0; r < 16; ++r) { const int kp0 = e0 + 16 * (r >> 3) + (r & 7);
;                         if (kp0 <= tq) atomicAdd((unsigned*)&hrow[ord_key(acc0[r]) >> 24], 1u);
;                         if (kp0 + 32 <= tq) atomicAdd((unsigned*)&hrow[ord_key(acc1[r]) >> 24], 1u); }
.Lb1_fast_hist:
	v_ashrrev_i32_e32 v0, 31, v88
	v_or_b32_e32 v0, v230, v0
	v_xor_b32_e32 v0, v0, v88
	v_lshrrev_b32_e32 v0, 24, v0
	v_lshl_add_u32 v0, v0, 2, v133
	ds_add_u32 v0, v228
	v_ashrrev_i32_e32 v1, 31, v92
	v_or_b32_e32 v1, v230, v1
	v_xor_b32_e32 v1, v1, v92
	v_lshrrev_b32_e32 v1, 24, v1
	v_lshl_add_u32 v1, v1, 2, v133
	ds_add_u32 v1, v228
	v_ashrrev_i32_e32 v2, 31, v89
	v_or_b32_e32 v2, v230, v2
	v_xor_b32_e32 v2, v2, v89
	v_lshrrev_b32_e32 v2, 24, v2
	v_lshl_add_u32 v2, v2, 2, v133
	ds_add_u32 v2, v228
	v_ashrrev_i32_e32 v3, 31, v93
	v_or_b32_e32 v3, v230, v3
	v_xor_b32_e32 v3, v3, v93
	v_lshrrev_b32_e32 v3, 24, v3
	v_lshl_add_u32 v3, v3, 2, v133
	ds_add_u32 v3, v228
	v_ashrrev_i32_e32 v4, 31, v90
	v_or_b32_e32 v4, v230, v4
	v_xor_b32_e32 v4, v4, v90
	v_lshrrev_b32_e32 v4, 24, v4
	v_lshl_add_u32 v4, v4, 2, v133
	ds_add_u32 v4, v228
	v_ashrrev_i32_e32 v5, 31, v94
	v_or_b32_e32 v5, v230, v5
	v_xor_b32_e32 v5, v5, v94
	v_lshrrev_b32_e32 v5, 24, v5
	v_lshl_add_u32 v5, v5, 2, v133
	ds_add_u32 v5, v228
	v_ashrrev_i32_e32 v6, 31, v91
	v_or_b32_e32 v6, v230, v6
	v_xor_b32_e32 v6, v6, v91
	v_lshrrev_b32_e32 v6, 24, v6
	v_lshl_add_u32 v6, v6, 2, v133
	ds_add_u32 v6, v228
	v_ashrrev_i32_e32 v7, 31, v95
	v_or_b32_e32 v7, v230, v7
	v_xor_b32_e32 v7, v7, v95
	v_lshrrev_b32_e32 v7, 24, v7
	v_lshl_add_u32 v7, v7, 2, v133
	ds_add_u32 v7, v228
	v_ashrrev_i32_e32 v8, 31, v80
	v_or_b32_e32 v8, v230, v8
	v_xor_b32_e32 v8, v8, v80
	v_lshrrev_b32_e32 v8, 24, v8
	v_lshl_add_u32 v8, v8, 2, v133
	ds_add_u32 v8, v228
	v_ashrrev_i32_e32 v9, 31, v84
	v_or_b32_e32 v9, v230, v9
	v_xor_b32_e32 v9, v9, v84
	v_lshrrev_b32_e32 v9, 24, v9
	v_lshl_add_u32 v9, v9, 2, v133
	ds_add_u32 v9, v228
	v_ashrrev_i32_e32 v10, 31, v81
	v_or_b32_e32 v10, v230, v10
	v_xor_b32_e32 v10, v10, v81
	v_lshrrev_b32_e32 v10, 24, v10
	v_lshl_add_u32 v10, v10, 2, v133
	ds_add_u32 v10, v228
	v_ashrrev_i32_e32 v11, 31, v85
	v_or_b32_e32 v11, v230, v11
	v_xor_b32_e32 v11, v11, v85
	v_lshrrev_b32_e32 v11, 24, v11
	v_lshl_add_u32 v11, v11, 2, v133
	ds_add_u32 v11, v228
	v_ashrrev_i32_e32 v12, 31, v82
	v_or_b32_e32 v12, v230, v12
	v_xor_b32_e32 v12, v12, v82
	v_lshrrev_b32_e32 v12, 24, v12
	v_lshl_add_u32 v12, v12, 2, v133
	ds_add_u32 v12, v228
	v_ashrrev_i32_e32 v13, 31, v86
	v_or_b32_e32 v13, v230, v13
	v_xor_b32_e32 v13, v13, v86
	v_lshrrev_b32_e32 v13, 24, v13
	v_lshl_add_u32 v13, v13, 2, v133
	ds_add_u32 v13, v228
	v_ashrrev_i32_e32 v14, 31, v83
	v_or_b32_e32 v14, v230, v14
	v_xor_b32_e32 v14, v14, v83
	v_lshrrev_b32_e32 v14, 24, v14
	v_lshl_add_u32 v14, v14, 2, v133
	ds_add_u32 v14, v228
	v_ashrrev_i32_e32 v15, 31, v87
	v_or_b32_e32 v15, v230, v15
	v_xor_b32_e32 v15, v15, v87
	v_lshrrev_b32_e32 v15, 24, v15
	v_lshl_add_u32 v15, v15, 2, v133
	ds_add_u32 v15, v228
	v_ashrrev_i32_e32 v0, 31, v72
	v_or_b32_e32 v0, v230, v0
	v_xor_b32_e32 v0, v0, v72
	v_lshrrev_b32_e32 v0, 24, v0
	v_lshl_add_u32 v0, v0, 2, v133
	ds_add_u32 v0, v228
	v_ashrrev_i32_e32 v1, 31, v76
	v_or_b32_e32 v1, v230, v1
	v_xor_b32_e32 v1, v1, v76
	v_lshrrev_b32_e32 v1, 24, v1
	v_lshl_add_u32 v1, v1, 2, v133
	ds_add_u32 v1, v228
	v_ashrrev_i32_e32 v2, 31, v73
	v_or_b32_e32 v2, v230, v2
	v_xor_b32_e32 v2, v2, v73
	v_lshrrev_b32_e32 v2, 24, v2
	v_lshl_add_u32 v2, v2, 2, v133
	ds_add_u32 v2, v228
	v_ashrrev_i32_e32 v3, 31, v77
	v_or_b32_e32 v3, v230, v3
	v_xor_b32_e32 v3, v3, v77
	v_lshrrev_b32_e32 v3, 24, v3
	v_lshl_add_u32 v3, v3, 2, v133
	ds_add_u32 v3, v228
	v_ashrrev_i32_e32 v4, 31, v74
	v_or_b32_e32 v4, v230, v4
	v_xor_b32_e32 v4, v4, v74
	v_lshrrev_b32_e32 v4, 24, v4
	v_lshl_add_u32 v4, v4, 2, v133
	ds_add_u32 v4, v228
	v_ashrrev_i32_e32 v5, 31, v78
	v_or_b32_e32 v5, v230, v5
	v_xor_b32_e32 v5, v5, v78
	v_lshrrev_b32_e32 v5, 24, v5
	v_lshl_add_u32 v5, v5, 2, v133
	ds_add_u32 v5, v228
	v_ashrrev_i32_e32 v6, 31, v75
	v_or_b32_e32 v6, v230, v6
	v_xor_b32_e32 v6, v6, v75
	v_lshrrev_b32_e32 v6, 24, v6
	v_lshl_add_u32 v6, v6, 2, v133
	ds_add_u32 v6, v228
	v_ashrrev_i32_e32 v7, 31, v79
	v_or_b32_e32 v7, v230, v7
	v_xor_b32_e32 v7, v7, v79
	v_lshrrev_b32_e32 v7, 24, v7
	v_lshl_add_u32 v7, v7, 2, v133
	ds_add_u32 v7, v228
	v_ashrrev_i32_e32 v8, 31, v64
	v_or_b32_e32 v8, v230, v8
	v_xor_b32_e32 v8, v8, v64
	v_lshrrev_b32_e32 v8, 24, v8
	v_lshl_add_u32 v8, v8, 2, v133
	ds_add_u32 v8, v228
	v_ashrrev_i32_e32 v9, 31, v68
	v_or_b32_e32 v9, v230, v9
	v_xor_b32_e32 v9, v9, v68
	v_lshrrev_b32_e32 v9, 24, v9
	v_lshl_add_u32 v9, v9, 2, v133
	ds_add_u32 v9, v228
	v_ashrrev_i32_e32 v10, 31, v65
	v_or_b32_e32 v10, v230, v10
	v_xor_b32_e32 v10, v10, v65
	v_lshrrev_b32_e32 v10, 24, v10
	v_lshl_add_u32 v10, v10, 2, v133
	ds_add_u32 v10, v228
	v_ashrrev_i32_e32 v11, 31, v69
	v_or_b32_e32 v11, v230, v11
	v_xor_b32_e32 v11, v11, v69
	v_lshrrev_b32_e32 v11, 24, v11
	v_lshl_add_u32 v11, v11, 2, v133
	ds_add_u32 v11, v228
	v_ashrrev_i32_e32 v12, 31, v66
	v_or_b32_e32 v12, v230, v12
	v_xor_b32_e32 v12, v12, v66
	v_lshrrev_b32_e32 v12, 24, v12
	v_lshl_add_u32 v12, v12, 2, v133
	ds_add_u32 v12, v228
	v_ashrrev_i32_e32 v13, 31, v70
	v_or_b32_e32 v13, v230, v13
	v_xor_b32_e32 v13, v13, v70
	v_lshrrev_b32_e32 v13, 24, v13
	v_lshl_add_u32 v13, v13, 2, v133
	ds_add_u32 v13, v228
	v_ashrrev_i32_e32 v14, 31, v67
	v_or_b32_e32 v14, v230, v14
	v_xor_b32_e32 v14, v14, v67
	v_lshrrev_b32_e32 v14, 24, v14
	v_lshl_add_u32 v14, v14, 2, v133
	ds_add_u32 v14, v228
	v_ashrrev_i32_e32 v15, 31, v71
	v_or_b32_e32 v15, v230, v15
	v_xor_b32_e32 v15, v15, v71
	v_lshrrev_b32_e32 v15, 24, v15
	v_lshl_add_u32 v15, v15, 2, v133
	ds_add_u32 v15, v228
	s_branch .LBB0_407
